# P3: half the workgroups (unit bit 3 clear) preload x into accumulators, the other half add x in the epilogue, to overlap HBM x reads with the other half's K-loop
# baseline (speedup 1.0000x reference)
.LBB0_311:
	s_waitcnt vmcnt(0)
	s_waitcnt lgkmcnt(0)
	s_barrier
	s_cmpk_gt_u32 s2, 0xff
	s_cbranch_scc1 .Lxa_skip
	s_bitcmp1_b32 s2, 3
	s_cbranch_scc1 .Lxa_skip
	v_readfirstlane_b32 s4, v254
	s_and_b32 s5, s2, 7
	s_lshr_b32 s4, s4, 6
	s_lshl_b32 s5, s5, 3
	s_bfe_u32 s6, s2, 0x30003
	s_add_i32 s5, s5, s6
	s_lshr_b32 s6, s2, 6
	s_lshl_b32 s5, s5, 8
	s_lshr_b32 s7, s4, 2
	s_lshl_b32 s7, s7, 6
	s_add_i32 s5, s5, s7
	s_lshl_b32 s6, s6, 8
	s_and_b32 s7, s4, 3
	s_lshl_b32 s7, s7, 6
	s_add_i32 s6, s6, s7
	v_and_b32_e32 v200, 15, v254
	v_bfe_u32 v201, v254, 4, 2
	v_or_b32_e32 v200, s5, v200
	v_lshl_or_b32 v201, v201, 3, s6
	v_lshlrev_b32_e32 v200, 10, v200
	v_add_u32_e32 v200, v200, v201
	v_lshlrev_b32_e32 v200, 2, v200
	v_add_u32_e32 v201, 0x10000, v200
	v_add_u32_e32 v202, 0x20000, v200
	v_add_u32_e32 v203, 0x30000, v200
	v_add_u32_e32 v204, 0x80000, v200
	v_add_u32_e32 v205, 0x90000, v200
	v_add_u32_e32 v206, 0xa0000, v200
	v_add_u32_e32 v207, 0xb0000, v200
	s_cmp_eq_u32 s4, 0
	s_cbranch_scc1 .Lxa_skip
	global_load_dwordx4 v[124:127], v200, s[12:13] nt
	global_load_dwordx4 v[120:123], v200, s[12:13] offset:16 nt
	global_load_dwordx4 v[116:119], v200, s[12:13] offset:128 nt
	global_load_dwordx4 v[112:115], v200, s[12:13] offset:144 nt
	global_load_dwordx4 v[108:111], v201, s[12:13] nt
	global_load_dwordx4 v[104:107], v201, s[12:13] offset:16 nt
	global_load_dwordx4 v[100:103], v201, s[12:13] offset:128 nt
	global_load_dwordx4 v[96:99], v201, s[12:13] offset:144 nt
	global_load_dwordx4 v[92:95], v202, s[12:13] nt
	global_load_dwordx4 v[88:91], v202, s[12:13] offset:16 nt
	global_load_dwordx4 v[84:87], v202, s[12:13] offset:128 nt
	global_load_dwordx4 v[80:83], v202, s[12:13] offset:144 nt
	global_load_dwordx4 v[76:79], v203, s[12:13] nt
	global_load_dwordx4 v[72:75], v203, s[12:13] offset:16 nt
	global_load_dwordx4 v[68:71], v203, s[12:13] offset:128 nt
	global_load_dwordx4 v[64:67], v203, s[12:13] offset:144 nt
	global_load_dwordx4 v[60:63], v204, s[12:13] nt
	global_load_dwordx4 v[56:59], v204, s[12:13] offset:16 nt
	global_load_dwordx4 v[52:55], v204, s[12:13] offset:128 nt
	global_load_dwordx4 v[48:51], v204, s[12:13] offset:144 nt
	global_load_dwordx4 v[44:47], v205, s[12:13] nt
	global_load_dwordx4 v[40:43], v205, s[12:13] offset:16 nt
	global_load_dwordx4 v[36:39], v205, s[12:13] offset:128 nt
	global_load_dwordx4 v[32:35], v205, s[12:13] offset:144 nt
	global_load_dwordx4 v[28:31], v206, s[12:13] nt
	global_load_dwordx4 v[24:27], v206, s[12:13] offset:16 nt
	global_load_dwordx4 v[20:23], v206, s[12:13] offset:128 nt

.LBB0_363:
	s_or_b64 exec, exec, s[0:1]
	s_waitcnt vmcnt(1)
	v_mov_b32_e32 v144, v254
	s_waitcnt lgkmcnt(0)
	v_cndmask_b32_e64 v240, 0, 1, s[94:95]
	s_barrier
	s_cmpk_gt_u32 s2, 0xff
	s_cbranch_scc1 .Lxb_done
	s_bitcmp1_b32 s2, 3
	s_cbranch_scc1 .Lxb_zero
	v_readfirstlane_b32 s4, v254
	s_nop 0
	s_lshr_b32 s4, s4, 6
	s_cmp_lg_u32 s4, 0
	s_cbranch_scc1 .Lxb_low
	global_load_dwordx4 v[124:127], v200, s[12:13] nt
	global_load_dwordx4 v[120:123], v200, s[12:13] offset:16 nt
	global_load_dwordx4 v[116:119], v200, s[12:13] offset:128 nt
	global_load_dwordx4 v[112:115], v200, s[12:13] offset:144 nt
	global_load_dwordx4 v[108:111], v201, s[12:13] nt
	global_load_dwordx4 v[104:107], v201, s[12:13] offset:16 nt
	global_load_dwordx4 v[100:103], v201, s[12:13] offset:128 nt
	global_load_dwordx4 v[96:99], v201, s[12:13] offset:144 nt
	global_load_dwordx4 v[92:95], v202, s[12:13] nt
	global_load_dwordx4 v[88:91], v202, s[12:13] offset:16 nt
	global_load_dwordx4 v[84:87], v202, s[12:13] offset:128 nt
	global_load_dwordx4 v[80:83], v202, s[12:13] offset:144 nt
	global_load_dwordx4 v[76:79], v203, s[12:13] nt
	global_load_dwordx4 v[72:75], v203, s[12:13] offset:16 nt
	global_load_dwordx4 v[68:71], v203, s[12:13] offset:128 nt
	global_load_dwordx4 v[64:67], v203, s[12:13] offset:144 nt
	global_load_dwordx4 v[60:63], v204, s[12:13] nt
	global_load_dwordx4 v[56:59], v204, s[12:13] offset:16 nt
	global_load_dwordx4 v[52:55], v204, s[12:13] offset:128 nt
	global_load_dwordx4 v[48:51], v204, s[12:13] offset:144 nt
	global_load_dwordx4 v[44:47], v205, s[12:13] nt
	global_load_dwordx4 v[40:43], v205, s[12:13] offset:16 nt
	global_load_dwordx4 v[36:39], v205, s[12:13] offset:128 nt
	global_load_dwordx4 v[32:35], v205, s[12:13] offset:144 nt
	global_load_dwordx4 v[28:31], v206, s[12:13] nt
	global_load_dwordx4 v[24:27], v206, s[12:13] offset:16 nt
	global_load_dwordx4 v[20:23], v206, s[12:13] offset:128 nt
.Lxb_low:
	global_load_dwordx4 v[16:19], v206, s[12:13] offset:144 nt
	global_load_dwordx4 v[12:15], v207, s[12:13] nt
	global_load_dwordx4 v[8:11], v207, s[12:13] offset:16 nt
	global_load_dwordx4 v[4:7], v207, s[12:13] offset:128 nt
	global_load_dwordx4 v[0:3], v207, s[12:13] offset:144 nt
	s_branch .Lxb_done
.Lxb_zero:
	v_mov_b64_e32 v[0:1], 0
	v_mov_b64_e32 v[2:3], 0
	v_mov_b64_e32 v[4:5], 0
	v_mov_b64_e32 v[6:7], 0
	v_mov_b64_e32 v[8:9], 0
	v_mov_b64_e32 v[10:11], 0
	v_mov_b64_e32 v[12:13], 0
	v_mov_b64_e32 v[14:15], 0
	v_mov_b64_e32 v[16:17], 0
	v_mov_b64_e32 v[18:19], 0
	v_mov_b64_e32 v[20:21], 0
	v_mov_b64_e32 v[22:23], 0
	v_mov_b64_e32 v[24:25], 0
	v_mov_b64_e32 v[26:27], 0
	v_mov_b64_e32 v[28:29], 0
	v_mov_b64_e32 v[30:31], 0
	v_mov_b64_e32 v[32:33], 0
	v_mov_b64_e32 v[34:35], 0
	v_mov_b64_e32 v[36:37], 0
	v_mov_b64_e32 v[38:39], 0
	v_mov_b64_e32 v[40:41], 0
	v_mov_b64_e32 v[42:43], 0
	v_mov_b64_e32 v[44:45], 0
	v_mov_b64_e32 v[46:47], 0
	v_mov_b64_e32 v[48:49], 0
	v_mov_b64_e32 v[50:51], 0
	v_mov_b64_e32 v[52:53], 0
	v_mov_b64_e32 v[54:55], 0
	v_mov_b64_e32 v[56:57], 0
	v_mov_b64_e32 v[58:59], 0
	v_mov_b64_e32 v[60:61], 0
	v_mov_b64_e32 v[62:63], 0
	v_mov_b64_e32 v[64:65], 0
	v_mov_b64_e32 v[66:67], 0
	v_mov_b64_e32 v[68:69], 0
	v_mov_b64_e32 v[70:71], 0
	v_mov_b64_e32 v[72:73], 0
	v_mov_b64_e32 v[74:75], 0
	v_mov_b64_e32 v[76:77], 0
	v_mov_b64_e32 v[78:79], 0
	v_mov_b64_e32 v[80:81], 0
	v_mov_b64_e32 v[82:83], 0
	v_mov_b64_e32 v[84:85], 0
	v_mov_b64_e32 v[86:87], 0
	v_mov_b64_e32 v[88:89], 0
	v_mov_b64_e32 v[90:91], 0
	v_mov_b64_e32 v[92:93], 0
	v_mov_b64_e32 v[94:95], 0
	v_mov_b64_e32 v[96:97], 0
	v_mov_b64_e32 v[98:99], 0
	v_mov_b64_e32 v[100:101], 0
	v_mov_b64_e32 v[102:103], 0
	v_mov_b64_e32 v[104:105], 0
	v_mov_b64_e32 v[106:107], 0
	v_mov_b64_e32 v[108:109], 0
	v_mov_b64_e32 v[110:111], 0
	v_mov_b64_e32 v[112:113], 0
	v_mov_b64_e32 v[114:115], 0
	v_mov_b64_e32 v[116:117], 0
	v_mov_b64_e32 v[118:119], 0
	v_mov_b64_e32 v[120:121], 0
	v_mov_b64_e32 v[122:123], 0
	v_mov_b64_e32 v[124:125], 0
	v_mov_b64_e32 v[126:127], 0

.LBB0_385:
	s_bitcmp1_b32 s2, 3
	s_cbranch_scc1 .Lxe_start
	v_mov_b32_e32 v140, v144
	s_lshl_b32 s9, s44, 8
	v_readfirstlane_b32 s8, v140
	s_bfe_u32 s29, s8, 0x20006
	s_ashr_i32 s8, s8, 2
	s_andn2_b32 s8, s8, 63
	s_add_i32 s8, s8, s9
	v_and_or_b32 v142, v140, 15, s8
	s_lshl_b32 s8, s20, 8
	s_lshl_b32 s9, s29, 6
	v_bfe_u32 v149, v140, 4, 2
	s_or_b32 s8, s9, s8
	v_lshl_or_b32 v140, v149, 3, s8
	v_ashrrev_i32_e32 v143, 31, v142
	v_ashrrev_i32_e32 v141, 31, v140
	v_lshlrev_b64 v[150:151], 10, v[142:143]
	v_lshl_add_u64 v[158:159], v[150:151], 0, v[140:141]
	v_lshl_add_u64 v[160:161], v[158:159], 2, s[12:13]
	v_lshl_add_u64 v[158:159], v[158:159], 1, s[16:17]
	s_lshl_b32 s44, s20, 2
	v_cmp_eq_u32_e32 vcc, 0, v149
	s_ashr_i32 s45, s44, 31
	v_mov_b64_e32 v[152:153], v[126:127]
	v_mov_b64_e32 v[150:151], v[124:125]
	v_mov_b64_e32 v[156:157], v[122:123]
	v_mov_b64_e32 v[154:155], v[120:121]
	v_cvt_pk_bf16_f32 v120, v150, v151
	v_cvt_pk_bf16_f32 v121, v152, v153
	v_cvt_pk_bf16_f32 v122, v154, v155
	v_cvt_pk_bf16_f32 v123, v156, v157
	global_store_dwordx4 v[158:159], v[120:123], off
	s_nop 0
	v_mul_f32_e32 v151, v151, v151
	v_mul_f32_e32 v153, v153, v153
	v_mul_f32_e32 v155, v155, v155
	v_mul_f32_e32 v157, v157, v157
	v_fmac_f32_e32 v151, v150, v150
	v_fmac_f32_e32 v153, v152, v152
	v_fmac_f32_e32 v155, v154, v154
	v_fmac_f32_e32 v157, v156, v156
	v_add_f32_e32 v150, v151, v153
	v_add_f32_e32 v151, v155, v157
	v_add_f32_e32 v150, v150, v151
	v_mov_b64_e32 v[120:121], v[114:115]
	v_mov_b64_e32 v[122:123], v[112:113]
	v_mul_f32_e32 v112, v117, v117
	v_mul_f32_e32 v113, v119, v119
	v_mul_f32_e32 v114, v123, v123
	v_mul_f32_e32 v115, v121, v121
	v_fmac_f32_e32 v112, v116, v116
	v_fmac_f32_e32 v113, v118, v118
	v_fmac_f32_e32 v114, v122, v122
	v_fmac_f32_e32 v115, v120, v120
	v_add_f32_e32 v112, v112, v113
	v_add_f32_e32 v113, v114, v115
	v_add_f32_e32 v112, v112, v113
	v_add_f32_e32 v112, v150, v112
	ds_bpermute_b32 v113, v193, v112
	v_cvt_pk_bf16_f32 v114, v116, v117
	v_cvt_pk_bf16_f32 v115, v118, v119
	v_cvt_pk_bf16_f32 v116, v122, v123
	v_cvt_pk_bf16_f32 v117, v120, v121
	s_waitcnt lgkmcnt(0)
	v_add_f32_e32 v112, v112, v113
	ds_bpermute_b32 v113, v194, v112
	global_store_dwordx4 v[158:159], v[114:117], off offset:64
	s_and_saveexec_b64 s[46:47], vcc
	s_cbranch_execz .LBB0_387
	v_lshlrev_b64 v[114:115], 6, v[142:143]
	v_lshl_add_u64 v[114:115], s[6:7], 0, v[114:115]
	v_lshl_add_u64 v[114:115], s[44:45], 2, v[114:115]
	s_lshl_b32 s20, s29, 2
	v_lshl_add_u64 v[114:115], v[114:115], 0, s[20:21]
	s_waitcnt lgkmcnt(0)
	v_add_f32_e32 v112, v112, v113
	global_store_dword v[114:115], v112, off

.Lxe_399:
	s_or_b64 exec, exec, s[46:47]
	v_add_u32_e32 v16, 0xb0, v142
	s_waitcnt lgkmcnt(0)
	v_ashrrev_i32_e32 v17, 31, v16
	v_lshlrev_b64 v[18:19], 10, v[16:17]
	v_lshl_add_u64 v[26:27], v[18:19], 0, v[140:141]
	v_lshl_add_u64 v[28:29], v[26:27], 2, s[12:13]
	global_load_dwordx4 v[18:21], v[28:29], off nt
	global_load_dwordx4 v[22:25], v[28:29], off offset:16 nt
	v_lshl_add_u64 v[26:27], v[26:27], 1, s[16:17]
	s_waitcnt vmcnt(1)
	v_pk_add_f32 v[20:21], v[14:15], v[20:21]
	v_pk_add_f32 v[18:19], v[12:13], v[18:19]
	s_waitcnt vmcnt(0)
	v_pk_add_f32 v[24:25], v[10:11], v[24:25]
	v_pk_add_f32 v[22:23], v[8:9], v[22:23]
	v_cvt_pk_bf16_f32 v8, v18, v19
	v_cvt_pk_bf16_f32 v9, v20, v21
	v_cvt_pk_bf16_f32 v10, v22, v23
	v_cvt_pk_bf16_f32 v11, v24, v25
	global_store_dwordx4 v[26:27], v[8:11], off
	global_load_dwordx4 v[8:11], v[28:29], off offset:128 nt
	s_nop 0
	global_load_dwordx4 v[12:15], v[28:29], off offset:144 nt
	v_mul_f32_e32 v19, v19, v19
	v_mul_f32_e32 v21, v21, v21
	v_mul_f32_e32 v23, v23, v23
	v_mul_f32_e32 v25, v25, v25
	v_fmac_f32_e32 v19, v18, v18
	v_fmac_f32_e32 v21, v20, v20
	v_fmac_f32_e32 v23, v22, v22
	v_fmac_f32_e32 v25, v24, v24
	v_add_f32_e32 v18, v19, v21
	v_add_f32_e32 v19, v23, v25
	v_add_f32_e32 v18, v18, v19
	s_waitcnt vmcnt(1)
	v_pk_add_f32 v[6:7], v[6:7], v[10:11]
	v_pk_add_f32 v[4:5], v[4:5], v[8:9]
	s_waitcnt vmcnt(0)
	v_pk_add_f32 v[8:9], v[2:3], v[14:15]
	v_pk_add_f32 v[10:11], v[0:1], v[12:13]
	v_mul_f32_e32 v0, v5, v5
	v_mul_f32_e32 v1, v7, v7
	v_mul_f32_e32 v2, v11, v11
	v_mul_f32_e32 v3, v9, v9
	v_fmac_f32_e32 v0, v4, v4
	v_fmac_f32_e32 v1, v6, v6
	v_fmac_f32_e32 v2, v10, v10
	v_fmac_f32_e32 v3, v8, v8
	v_add_f32_e32 v0, v0, v1
	v_add_f32_e32 v1, v2, v3
	v_add_f32_e32 v0, v0, v1
	v_add_f32_e32 v0, v18, v0
	ds_bpermute_b32 v1, v193, v0
	v_cvt_pk_bf16_f32 v2, v4, v5
	v_cvt_pk_bf16_f32 v3, v6, v7
	v_cvt_pk_bf16_f32 v4, v10, v11
	v_cvt_pk_bf16_f32 v5, v8, v9
	s_waitcnt lgkmcnt(0)
	v_add_f32_e32 v0, v0, v1
	ds_bpermute_b32 v1, v194, v0
	global_store_dwordx4 v[26:27], v[2:5], off offset:64
	s_and_saveexec_b64 s[46:47], vcc
	s_cbranch_execz .LBB0_401
	v_lshlrev_b64 v[2:3], 6, v[16:17]
	v_lshl_add_u64 v[2:3], s[6:7], 0, v[2:3]
	v_lshl_add_u64 v[2:3], s[44:45], 2, v[2:3]
	s_lshl_b32 s20, s29, 2
	v_lshl_add_u64 v[2:3], v[2:3], 0, s[20:21]
	s_waitcnt lgkmcnt(0)
	v_add_f32_e32 v0, v0, v1
	global_store_dword v[2:3], v0, off
	s_branch .LBB0_401
